# phase B sample-row split-K GEMM: 2-D task mapping (7 weight n-tiles x 2 m-tiles per block) cuts L2 weight traffic about 40 percent; all fragment loads in flight
# speedup vs baseline: 1.0123x; 1.0041x over previous
; __device__ __forceinline__ int lane_fresh() { int l; asm volatile("v_mbcnt_lo_u32_b32 %0, -1, 0\n\tv_mbcnt_hi_u32_b32 %0, -1, %0" : "=v"(l)); return l; }
; #define MFMA16(a, b, c) __builtin_amdgcn_mfma_f32_16x16x32_bf16((a), (b), (c), 0, 0, 0)
; template <int NT, class FA, class FB, class FL>
; __device__ __forceinline__ void skgemm(FA aptr, FB bptr, FL ldf, const int KS, const int wv) {
;   float* part = (float*)g_shm;
;   const int lane = lane_fresh(), fr = lane & 15, fq = lane >> 4;
;   __syncthreads();
; #pragma unroll
;   for (int i = 0; i < NT; ++i) {
;     f32x4 acc = {0.f, 0.f, 0.f, 0.f};
;     const int ld = ldf(i);
;     const u16* ap = aptr(i) + (size_t)fr * ld + wv * KS + fq * 8;
;     const u16* bp = bptr(i) + (size_t)fr * ld + wv * KS + fq * 8;
; #pragma unroll 8
;     for (int k = 0; k < KS; k += 32) acc = MFMA16(*(const bf16x8*)(bp + k), *(const bf16x8*)(ap + k), acc);
;     *(f32x4*)(part + ((i * 8 + wv) * 64 + lane) * 4) = acc;
;   }
;   __syncthreads();
; __device__ __forceinline__ void phaseB(const Params& p, const int wv, const int rep) {
;     ...
;   for (int gb = blockIdx.x; gb < 256; gb += gridDim.x) {
;     const int task0 = gb * 14, mt = task0 / 448, nt0 = task0 - mt * 448;
;     const u16* Ab = XN + (size_t)(TP + mt * 16) * 1024;
;     const u16* Bb = (const u16*)(ws + OFF_WIN) + (size_t)(nt0 * 16) * 1024;
;     skgemm<14>([&](int) { return Ab; }, [&](int i) { return Bb + (size_t)i * 16 * 1024; }, [&](int) { return 1024; }, 128, wv);
.LBB0_225:
	s_ashr_i32 s23, s43, 31
	s_lshr_b32 s23, s23, 27
	s_add_i32 s23, s43, s23
	s_ashr_i32 s26, s23, 5
	s_mul_i32 s22, s43, 14
	s_mul_i32 s23, s26, 0xfffffe40
	s_add_i32 s27, s23, s22
	s_lshl_b32 s22, s26, 4
	s_addk_i32 s22, 0x4000
	s_ashr_i32 s23, s22, 31
	s_lshl_b64 s[24:25], s[22:23], 11
	s_add_u32 s24, s48, s24
	s_addc_u32 s25, s49, s25
	s_lshl_b32 s28, s27, 4
	s_ashr_i32 s29, s28, 31
	v_mbcnt_lo_u32_b32 v56, -1, 0
	v_mbcnt_hi_u32_b32 v56, -1, v56
	s_lshl_b64 s[28:29], s[28:29], 11
	v_ashrrev_i32_e32 v0, 1, v56
	v_lshlrev_b32_e32 v2, 11, v56
	v_and_b32_e32 v0, -8, v0
	v_and_b32_e32 v52, 0x7800, v2
	s_add_u32 s28, s50, s28
	v_ashrrev_i32_e32 v1, 31, v0
	v_lshl_add_u64 v[2:3], s[24:25], 0, v[52:53]
	s_addc_u32 s29, s51, s29
	v_lshl_add_u64 v[2:3], v[2:3], 0, s[0:1]
	v_lshlrev_b64 v[0:1], 1, v[0:1]
	v_lshl_add_u64 v[86:87], v[2:3], 0, v[0:1]
	v_lshl_add_u64 v[2:3], s[28:29], 0, v[52:53]
	v_lshl_add_u64 v[2:3], v[2:3], 0, s[0:1]
	v_lshl_add_u64 v[54:55], v[2:3], 0, v[0:1]
	s_mov_b32 s23, 0x8000
	v_add_co_u32_e32 v8, vcc, s23, v54
	s_mov_b32 s23, 0x10000
	s_nop 0
	v_addc_co_u32_e32 v9, vcc, 0, v55, vcc
	s_waitcnt lgkmcnt(0)
	s_barrier
	s_lshr_b32 s23, s43, 6
	s_lshl_b32 s23, s23, 5
	s_addk_i32 s23, 0x4000
	s_lshl_b32 s24, s23, 11
	s_add_u32 s24, s48, s24
	s_addc_u32 s25, s49, 0
	s_and_b32 s27, s43, 63
	s_mul_i32 s27, s27, 7
	s_lshl_b32 s27, s27, 15
	s_add_u32 s28, s50, s27
	s_addc_u32 s29, s51, 0
	v_and_b32_e32 v248, 15, v56
	v_lshlrev_b32_e32 v248, 11, v248
	v_lshrrev_b32_e32 v249, 4, v56
	v_lshl_add_u32 v248, v249, 4, v248
	v_add_u32_e32 v248, s0, v248
	v_lshlrev_b32_e32 v249, 4, v56
	v_add_u32_e32 v249, s13, v249
	v_add_u32_e32 v62, 0x10000, v249
	global_load_dwordx4 v[0:3], v248, s[24:25]
	global_load_dwordx4 v[4:7], v248, s[24:25] offset:64
	global_load_dwordx4 v[8:11], v248, s[24:25] offset:128
	global_load_dwordx4 v[12:15], v248, s[24:25] offset:192
	global_load_dwordx4 v[64:67], v248, s[28:29]
	global_load_dwordx4 v[68:71], v248, s[28:29] offset:64
	global_load_dwordx4 v[72:75], v248, s[28:29] offset:128
	global_load_dwordx4 v[76:79], v248, s[28:29] offset:192
	s_add_u32 s28, s28, 0x8000
	s_addc_u32 s29, s29, 0
	global_load_dwordx4 v[80:83], v248, s[28:29]
	global_load_dwordx4 v[84:87], v248, s[28:29] offset:64
	global_load_dwordx4 v[88:91], v248, s[28:29] offset:128
	global_load_dwordx4 v[92:95], v248, s[28:29] offset:192
	s_add_u32 s28, s28, 0x8000
	s_addc_u32 s29, s29, 0
	global_load_dwordx4 v[96:99], v248, s[28:29]
	global_load_dwordx4 v[100:103], v248, s[28:29] offset:64
	global_load_dwordx4 v[104:107], v248, s[28:29] offset:128
	global_load_dwordx4 v[108:111], v248, s[28:29] offset:192
	s_add_u32 s28, s28, 0x8000
	s_addc_u32 s29, s29, 0
	global_load_dwordx4 v[112:115], v248, s[28:29]
	global_load_dwordx4 v[116:119], v248, s[28:29] offset:64
	global_load_dwordx4 v[120:123], v248, s[28:29] offset:128
	global_load_dwordx4 v[124:127], v248, s[28:29] offset:192
	s_add_u32 s28, s28, 0x8000
	s_addc_u32 s29, s29, 0
	global_load_dwordx4 v[128:131], v248, s[28:29]
	global_load_dwordx4 v[132:135], v248, s[28:29] offset:64
	global_load_dwordx4 v[136:139], v248, s[28:29] offset:128
	global_load_dwordx4 v[140:143], v248, s[28:29] offset:192
	s_add_u32 s28, s28, 0x8000
	s_addc_u32 s29, s29, 0
	global_load_dwordx4 v[144:147], v248, s[28:29]
	global_load_dwordx4 v[148:151], v248, s[28:29] offset:64
	global_load_dwordx4 v[152:155], v248, s[28:29] offset:128
	global_load_dwordx4 v[156:159], v248, s[28:29] offset:192
	s_add_u32 s28, s28, 0x8000
	s_addc_u32 s29, s29, 0
	global_load_dwordx4 v[160:163], v248, s[28:29]
	global_load_dwordx4 v[164:167], v248, s[28:29] offset:64
	global_load_dwordx4 v[168:171], v248, s[28:29] offset:128
	global_load_dwordx4 v[172:175], v248, s[28:29] offset:192
	s_add_u32 s28, s28, 0x8000
	s_addc_u32 s29, s29, 0
	s_add_u32 s24, s24, 0x8000
	s_addc_u32 s25, s25, 0
	global_load_dwordx4 v[16:19], v248, s[24:25]
	global_load_dwordx4 v[20:23], v248, s[24:25] offset:64
	global_load_dwordx4 v[24:27], v248, s[24:25] offset:128
	global_load_dwordx4 v[28:31], v248, s[24:25] offset:192
	s_waitcnt vmcnt(31)
	v_mfma_f32_16x16x32_bf16 v[192:195], v[64:67], v[0:3], 0
	s_waitcnt vmcnt(30)
	v_mfma_f32_16x16x32_bf16 v[192:195], v[68:71], v[4:7], v[192:195]
	s_waitcnt vmcnt(29)
	v_mfma_f32_16x16x32_bf16 v[192:195], v[72:75], v[8:11], v[192:195]
	s_waitcnt vmcnt(28)
	v_mfma_f32_16x16x32_bf16 v[192:195], v[76:79], v[12:15], v[192:195]
	s_waitcnt vmcnt(27)
	v_mfma_f32_16x16x32_bf16 v[196:199], v[80:83], v[0:3], 0
	s_waitcnt vmcnt(26)
	v_mfma_f32_16x16x32_bf16 v[196:199], v[84:87], v[4:7], v[196:199]
	s_waitcnt vmcnt(25)
	v_mfma_f32_16x16x32_bf16 v[196:199], v[88:91], v[8:11], v[196:199]
	s_waitcnt vmcnt(24)
	v_mfma_f32_16x16x32_bf16 v[196:199], v[92:95], v[12:15], v[196:199]
	s_waitcnt vmcnt(23)
	v_mfma_f32_16x16x32_bf16 v[200:203], v[96:99], v[0:3], 0
	s_waitcnt vmcnt(22)
	v_mfma_f32_16x16x32_bf16 v[200:203], v[100:103], v[4:7], v[200:203]
	s_waitcnt vmcnt(21)
; #define MFMA16(a, b, c) __builtin_amdgcn_mfma_f32_16x16x32_bf16((a), (b), (c), 0, 0, 0)
; template <int NT, class FA, class FB, class FL>
; __device__ __forceinline__ void skgemm(FA aptr, FB bptr, FL ldf, const int KS, const int wv) {
;     ...
;   for (int i = 0; i < NT; ++i) {
;     f32x4 acc = {0.f, 0.f, 0.f, 0.f};
;     const int ld = ldf(i);
;     const u16* ap = aptr(i) + (size_t)fr * ld + wv * KS + fq * 8;
;     const u16* bp = bptr(i) + (size_t)fr * ld + wv * KS + fq * 8;
; #pragma unroll 8
;     for (int k = 0; k < KS; k += 32) acc = MFMA16(*(const bf16x8*)(bp + k), *(const bf16x8*)(ap + k), acc);
;     *(f32x4*)(part + ((i * 8 + wv) * 64 + lane) * 4) = acc;
;   }
;   __syncthreads();
; __device__ __forceinline__ void phaseB(const Params& p, const int wv, const int rep) {
;     ...
;   for (int gb = blockIdx.x; gb < 256; gb += gridDim.x) {
;     const int task0 = gb * 14, mt = task0 / 448, nt0 = task0 - mt * 448;
;     const u16* Ab = XN + (size_t)(TP + mt * 16) * 1024;
;     const u16* Bb = (const u16*)(ws + OFF_WIN) + (size_t)(nt0 * 16) * 1024;
;     skgemm<14>([&](int) { return Ab; }, [&](int i) { return Bb + (size_t)i * 16 * 1024; }, [&](int) { return 1024; }, 128, wv);
	v_mfma_f32_16x16x32_bf16 v[200:203], v[104:107], v[8:11], v[200:203]
	s_waitcnt vmcnt(20)
	v_mfma_f32_16x16x32_bf16 v[200:203], v[108:111], v[12:15], v[200:203]
	ds_write_b128 v249, v[192:195]
	s_waitcnt vmcnt(19)
	v_mfma_f32_16x16x32_bf16 v[204:207], v[112:115], v[0:3], 0
	s_waitcnt vmcnt(18)
	v_mfma_f32_16x16x32_bf16 v[204:207], v[116:119], v[4:7], v[204:207]
	s_waitcnt vmcnt(17)
	v_mfma_f32_16x16x32_bf16 v[204:207], v[120:123], v[8:11], v[204:207]
	s_waitcnt vmcnt(16)
	v_mfma_f32_16x16x32_bf16 v[204:207], v[124:127], v[12:15], v[204:207]
	ds_write_b128 v249, v[196:199] offset:8192
	s_waitcnt vmcnt(15)
	v_mfma_f32_16x16x32_bf16 v[208:211], v[128:131], v[0:3], 0
	s_waitcnt vmcnt(14)
	v_mfma_f32_16x16x32_bf16 v[208:211], v[132:135], v[4:7], v[208:211]
	s_waitcnt vmcnt(13)
	v_mfma_f32_16x16x32_bf16 v[208:211], v[136:139], v[8:11], v[208:211]
	s_waitcnt vmcnt(12)
	v_mfma_f32_16x16x32_bf16 v[208:211], v[140:143], v[12:15], v[208:211]
	ds_write_b128 v249, v[200:203] offset:16384
	s_waitcnt vmcnt(11)
	v_mfma_f32_16x16x32_bf16 v[212:215], v[144:147], v[0:3], 0
	s_waitcnt vmcnt(10)
	v_mfma_f32_16x16x32_bf16 v[212:215], v[148:151], v[4:7], v[212:215]
	s_waitcnt vmcnt(9)
	v_mfma_f32_16x16x32_bf16 v[212:215], v[152:155], v[8:11], v[212:215]
	s_waitcnt vmcnt(8)
	v_mfma_f32_16x16x32_bf16 v[212:215], v[156:159], v[12:15], v[212:215]
	ds_write_b128 v249, v[204:207] offset:24576
	s_waitcnt vmcnt(7)
	v_mfma_f32_16x16x32_bf16 v[216:219], v[160:163], v[0:3], 0
	s_waitcnt vmcnt(6)
	v_mfma_f32_16x16x32_bf16 v[216:219], v[164:167], v[4:7], v[216:219]
	s_waitcnt vmcnt(5)
	v_mfma_f32_16x16x32_bf16 v[216:219], v[168:171], v[8:11], v[216:219]
	s_waitcnt vmcnt(4)
	v_mfma_f32_16x16x32_bf16 v[216:219], v[172:175], v[12:15], v[216:219]
	ds_write_b128 v249, v[208:211] offset:32768
	s_waitcnt vmcnt(3)
	v_mfma_f32_16x16x32_bf16 v[220:223], v[64:67], v[16:19], 0
	s_waitcnt vmcnt(2)
	v_mfma_f32_16x16x32_bf16 v[220:223], v[68:71], v[20:23], v[220:223]
	s_waitcnt vmcnt(1)
	v_mfma_f32_16x16x32_bf16 v[220:223], v[72:75], v[24:27], v[220:223]
	s_waitcnt vmcnt(0)
	v_mfma_f32_16x16x32_bf16 v[220:223], v[76:79], v[28:31], v[220:223]
	ds_write_b128 v249, v[212:215] offset:40960
	s_waitcnt vmcnt(3)
	v_mfma_f32_16x16x32_bf16 v[224:227], v[80:83], v[16:19], 0
	s_waitcnt vmcnt(2)
	v_mfma_f32_16x16x32_bf16 v[224:227], v[84:87], v[20:23], v[224:227]
	s_waitcnt vmcnt(1)
	v_mfma_f32_16x16x32_bf16 v[224:227], v[88:91], v[24:27], v[224:227]
	s_waitcnt vmcnt(0)
	v_mfma_f32_16x16x32_bf16 v[224:227], v[92:95], v[28:31], v[224:227]
	ds_write_b128 v249, v[216:219] offset:49152
	s_waitcnt vmcnt(3)
	v_mfma_f32_16x16x32_bf16 v[228:231], v[96:99], v[16:19], 0
	s_waitcnt vmcnt(2)
	v_mfma_f32_16x16x32_bf16 v[228:231], v[100:103], v[20:23], v[228:231]
	s_waitcnt vmcnt(1)
	v_mfma_f32_16x16x32_bf16 v[228:231], v[104:107], v[24:27], v[228:231]
	s_waitcnt vmcnt(0)
	v_mfma_f32_16x16x32_bf16 v[228:231], v[108:111], v[28:31], v[228:231]
	ds_write_b128 v249, v[220:223] offset:57344
	s_waitcnt vmcnt(3)
	v_mfma_f32_16x16x32_bf16 v[232:235], v[112:115], v[16:19], 0
	s_waitcnt vmcnt(2)
	v_mfma_f32_16x16x32_bf16 v[232:235], v[116:119], v[20:23], v[232:235]
	s_waitcnt vmcnt(1)
	v_mfma_f32_16x16x32_bf16 v[232:235], v[120:123], v[24:27], v[232:235]
	s_waitcnt vmcnt(0)
	v_mfma_f32_16x16x32_bf16 v[232:235], v[124:127], v[28:31], v[232:235]
	ds_write_b128 v62, v[224:227]
	s_waitcnt vmcnt(3)
	v_mfma_f32_16x16x32_bf16 v[236:239], v[128:131], v[16:19], 0
	s_waitcnt vmcnt(2)
	v_mfma_f32_16x16x32_bf16 v[236:239], v[132:135], v[20:23], v[236:239]
	s_waitcnt vmcnt(1)
	v_mfma_f32_16x16x32_bf16 v[236:239], v[136:139], v[24:27], v[236:239]
	s_waitcnt vmcnt(0)
	v_mfma_f32_16x16x32_bf16 v[236:239], v[140:143], v[28:31], v[236:239]
	ds_write_b128 v62, v[228:231] offset:8192
	s_waitcnt vmcnt(3)
	v_mfma_f32_16x16x32_bf16 v[240:243], v[144:147], v[16:19], 0
	s_waitcnt vmcnt(2)
	v_mfma_f32_16x16x32_bf16 v[240:243], v[148:151], v[20:23], v[240:243]
	s_waitcnt vmcnt(1)
	v_mfma_f32_16x16x32_bf16 v[240:243], v[152:155], v[24:27], v[240:243]
	s_waitcnt vmcnt(0)
	v_mfma_f32_16x16x32_bf16 v[240:243], v[156:159], v[28:31], v[240:243]
	ds_write_b128 v62, v[232:235] offset:16384
	s_waitcnt vmcnt(3)
	v_mfma_f32_16x16x32_bf16 v[244:247], v[160:163], v[16:19], 0
	s_waitcnt vmcnt(2)
	v_mfma_f32_16x16x32_bf16 v[244:247], v[164:167], v[20:23], v[244:247]
	s_waitcnt vmcnt(1)
	v_mfma_f32_16x16x32_bf16 v[244:247], v[168:171], v[24:27], v[244:247]
	s_waitcnt vmcnt(0)
	v_mfma_f32_16x16x32_bf16 v[244:247], v[172:175], v[28:31], v[244:247]
	ds_write_b128 v62, v[236:239] offset:24576
	s_andn2_b64 vcc, exec, s[4:5]
	s_nop 7
	ds_write_b128 v62, v[240:243] offset:32768
	ds_write_b128 v62, v[244:247] offset:40960
	s_waitcnt lgkmcnt(0)
	s_barrier
	s_cbranch_vccnz .LBB0_224
	s_ashr_i32 s23, s22, 11
	s_mul_hi_i32 s25, s23, 0x4800
	s_mulk_i32 s23, 0x4800
	s_add_u32 s24, s48, s23
	s_addc_u32 s25, s49, s25
	s_mul_i32 s23, s26, 0xffffe400
	s_mov_b32 s44, s15
	s_mov_b32 s45, s40
	s_branch .LBB0_229

; __device__ __forceinline__ int lane_fresh() { int l; asm volatile("v_mbcnt_lo_u32_b32 %0, -1, 0\n\tv_mbcnt_hi_u32_b32 %0, -1, %0" : "=v"(l)); return l; }
; __device__ __forceinline__ f32x4 skreduce(int i) {
;   const float* part = (const float*)g_shm;
;   const int lane = lane_fresh();
;   f32x4 s = {0.f, 0.f, 0.f, 0.f};
; #pragma unroll
;   for (int w = 0; w < 8; ++w) s += *(const f32x4*)(part + ((i * 8 + w) * 64 + lane) * 4);
;   return s;
; }
; __device__ __forceinline__ void phaseB(const Params& p, const int wv, const int rep) {
;     ...
;     for (int i = wv; i < 14; i += 8) {
;       const int lane_e = lane_fresh(), fr = lane_e & 15, fq = lane_e >> 4;
;       f32x4 a = skreduce(i);
;       int row = TP + mt * 16 + fr, col = (nt0 + i) * 16 + fq * 4;
;       switch (secB(col)) {
;         case 0: epiB<0>(p, row, col, a); break;
;         case 1: epiB<1>(p, row, col, a); break;
;         case 2: epiB<2>(p, row, col, a); break;
;         case 3: epiB<3>(p, row, col, a); break;
;         default: epiB<4>(p, row, col, a); break;
;       }
.LBB0_229:
	v_mbcnt_lo_u32_b32 v4, -1, 0
	v_mbcnt_hi_u32_b32 v4, -1, v4
	v_mbcnt_lo_u32_b32 v0, -1, 0
	v_mbcnt_hi_u32_b32 v0, -1, v0
	s_add_i32 s26, s41, s23
	s_add_i32 s98, s45, 8
	s_cmp_ge_u32 s98, 7
	s_cselect_b32 s99, 1, 0
	s_mul_i32 s26, s99, 7
	s_sub_u32 s98, s98, s26
	s_and_b32 s26, s43, 63
	s_mul_i32 s26, s26, 7
	s_add_i32 s26, s26, s98
	s_lshl_b32 s26, s26, 4
	s_lshr_b32 s98, s43, 6
	s_lshl_b32 s98, s98, 1
	s_add_i32 s98, s98, s99
	s_lshl_b32 s22, s98, 4
	s_addk_i32 s22, 0x4000
	v_lshl_add_u32 v5, v0, 4, s44
	ds_read_b128 v[0:3], v5
	ds_read_b128 v[6:9], v5 offset:1024
	ds_read_b128 v[10:13], v5 offset:2048
	ds_read_b128 v[14:17], v5 offset:3072
	s_waitcnt lgkmcnt(3)
	v_pk_add_f32 v[2:3], v[2:3], 0 op_sel_hi:[1,0]
	v_pk_add_f32 v[0:1], v[0:1], 0 op_sel_hi:[1,0]
	s_waitcnt lgkmcnt(2)
	v_pk_add_f32 v[2:3], v[2:3], v[8:9]
	v_pk_add_f32 v[6:7], v[0:1], v[6:7]
	s_waitcnt lgkmcnt(1)
	v_pk_add_f32 v[8:9], v[2:3], v[12:13]
	ds_read_b128 v[0:3], v5 offset:4096
	v_pk_add_f32 v[6:7], v[6:7], v[10:11]
	s_waitcnt lgkmcnt(1)
	v_pk_add_f32 v[10:11], v[8:9], v[16:17]
	v_pk_add_f32 v[14:15], v[6:7], v[14:15]
	ds_read_b128 v[6:9], v5 offset:5120
	s_waitcnt lgkmcnt(1)
	v_pk_add_f32 v[16:17], v[10:11], v[2:3]
	ds_read_b128 v[10:13], v5 offset:6144
	v_pk_add_f32 v[14:15], v[14:15], v[0:1]
	ds_read_b128 v[0:3], v5 offset:7168
	s_waitcnt lgkmcnt(2)
	v_pk_add_f32 v[6:7], v[14:15], v[6:7]
	v_pk_add_f32 v[8:9], v[16:17], v[8:9]
	s_waitcnt lgkmcnt(1)
	v_pk_add_f32 v[6:7], v[6:7], v[10:11]
	v_pk_add_f32 v[8:9], v[8:9], v[12:13]
	s_waitcnt lgkmcnt(0)
	v_pk_add_f32 v[0:1], v[6:7], v[0:1]
	v_and_or_b32 v6, v4, 15, s22
	v_ashrrev_i32_e32 v4, 2, v4
	v_and_b32_e32 v4, -4, v4
	v_add_u32_e32 v4, s26, v4
	s_movk_i32 s26, 0x1000
	v_cmp_gt_u32_e32 vcc, s26, v4
	s_movk_i32 s26, 0xdff
	v_pk_add_f32 v[2:3], v[8:9], v[2:3]
	v_cndmask_b32_e64 v5, 4, 3, vcc
	v_cmp_lt_u32_e32 vcc, s26, v4
	s_movk_i32 s26, 0x7ff
	s_nop 0
	v_cndmask_b32_e32 v5, 2, v5, vcc
	v_cmp_lt_u32_e32 vcc, s26, v4
	s_movk_i32 s26, 0x3ff
	s_nop 0
	v_cndmask_b32_e32 v5, 1, v5, vcc
	v_cmp_lt_i32_e32 vcc, s26, v4
	s_nop 1
	v_cndmask_b32_e32 v5, 0, v5, vcc
	v_cmp_lt_i32_e32 vcc, 1, v5
	s_and_saveexec_b64 s[26:27], vcc
	s_xor_b64 s[26:27], exec, s[26:27]
	s_cbranch_execz .LBB0_245
	v_cmp_lt_i32_e32 vcc, 2, v5
	s_and_saveexec_b64 s[28:29], vcc
	s_xor_b64 s[28:29], exec, s[28:29]
	s_cbranch_execz .LBB0_236
	v_cmp_ne_u32_e32 vcc, 3, v5
	s_and_saveexec_b64 s[30:31], vcc
	s_xor_b64 s[30:31], exec, s[30:31]
	s_cbranch_execz .LBB0_233
	v_mul_f32_e32 v0, 0xbfb8aa3b, v0
	v_mul_f32_e32 v1, 0xbfb8aa3b, v1
	v_mul_f32_e32 v2, 0xbfb8aa3b, v2
	v_mul_f32_e32 v3, 0xbfb8aa3b, v3
	v_exp_f32_e32 v0, v0
	v_exp_f32_e32 v1, v1
	v_exp_f32_e32 v2, v2
	v_exp_f32_e32 v3, v3
	v_add_f32_e32 v0, 1.0, v0
	v_add_f32_e32 v1, 1.0, v1
	v_add_f32_e32 v2, 1.0, v2
	v_add_f32_e32 v3, 1.0, v3
	v_rcp_f32_e32 v0, v0
	v_rcp_f32_e32 v1, v1
	v_rcp_f32_e32 v2, v2
	v_rcp_f32_e32 v3, v3
	s_movk_i32 s34, 0x1800
	v_cvt_pk_bf16_f32 v0, v0, v1
	v_ashrrev_i32_e32 v5, 31, v4
	v_cvt_pk_bf16_f32 v1, v2, v3
	v_mov_b64_e32 v[2:3], s[50:51]
	v_mad_i64_i32 v[2:3], s[34:35], v6, s34, v[2:3]
	v_lshl_add_u64 v[2:3], v[4:5], 1, v[2:3]
	v_add_co_u32_e32 v2, vcc, 0xb32c000, v2
	s_nop 1
	v_addc_co_u32_e32 v3, vcc, 0, v3, vcc
	global_store_dwordx2 v[2:3], v[0:1], off
